# v189 + P9 epilogue preamble: the 14 row-index ops only needed by the (never-taken here) recompute-scales branch moved into that branch
# baseline (speedup 1.0000x reference)
.LBB0_509:
	v_lshl_add_u32 v162, s8, 8, v177
	s_mov_b64 s[0:1], -1
	s_cmp_lg_u32 s8, s27
	v_ashrrev_i32_e32 v163, 31, v162
	s_cbranch_scc0 .LBB0_511
	v_or_b32_e32 v166, 16, v162
	v_or_b32_e32 v158, 32, v162
	v_or_b32_e32 v156, 48, v162
	v_add_u32_e32 v152, 0x80, v162
	v_add_u32_e32 v150, 0x90, v162
	v_add_u32_e32 v148, 0xa0, v162
	v_add_u32_e32 v146, 0xb0, v162
	v_ashrrev_i32_e32 v167, 31, v166
	v_ashrrev_i32_e32 v159, 31, v158
	v_ashrrev_i32_e32 v157, 31, v156
	v_ashrrev_i32_e32 v153, 31, v152
	v_ashrrev_i32_e32 v151, 31, v150
	v_ashrrev_i32_e32 v149, 31, v148
	v_ashrrev_i32_e32 v147, 31, v146
	v_lshlrev_b64 v[154:155], 7, v[162:163]
	v_lshlrev_b64 v[160:161], 7, v[166:167]
	v_lshl_add_u64 v[154:155], v[136:137], 0, v[154:155]
	v_lshl_add_u64 v[160:161], v[136:137], 0, v[160:161]
	global_load_dwordx4 v[168:171], v[154:155], off
	global_load_dwordx4 v[186:189], v[160:161], off
	global_load_dwordx4 v[190:193], v[154:155], off offset:16
	global_load_dwordx4 v[194:197], v[160:161], off offset:16
	v_lshlrev_b64 v[154:155], 7, v[158:159]
	v_lshlrev_b64 v[160:161], 7, v[156:157]
	v_lshl_add_u64 v[154:155], v[136:137], 0, v[154:155]
	v_lshl_add_u64 v[160:161], v[136:137], 0, v[160:161]
	global_load_dwordx4 v[198:201], v[154:155], off
	global_load_dwordx4 v[202:205], v[160:161], off
	global_load_dwordx4 v[206:209], v[154:155], off offset:16
	global_load_dwordx4 v[214:217], v[160:161], off offset:16
	v_lshlrev_b64 v[154:155], 7, v[152:153]
	v_lshlrev_b64 v[160:161], 7, v[150:151]
	v_lshl_add_u64 v[154:155], v[136:137], 0, v[154:155]
	v_lshl_add_u64 v[160:161], v[136:137], 0, v[160:161]
	global_load_dwordx4 v[218:221], v[154:155], off
	global_load_dwordx4 v[222:225], v[160:161], off
	global_load_dwordx4 v[226:229], v[154:155], off offset:16
	global_load_dwordx4 v[230:233], v[160:161], off offset:16
	v_lshlrev_b64 v[154:155], 7, v[148:149]
	v_lshlrev_b64 v[160:161], 7, v[146:147]
	v_lshl_add_u64 v[154:155], v[136:137], 0, v[154:155]
	v_lshl_add_u64 v[160:161], v[136:137], 0, v[160:161]
	global_load_dwordx4 v[234:237], v[154:155], off offset:16
	global_load_dwordx4 v[238:241], v[154:155], off
	global_load_dwordx4 v[242:245], v[160:161], off offset:16
	global_load_dwordx4 v[246:249], v[160:161], off
	v_mov_b64_e32 v[164:165], s[34:35]
	s_waitcnt vmcnt(0)
	v_mov_b32_e32 v155, v186
	v_mov_b32_e32 v154, v168
	v_mov_b32_e32 v186, v169
	v_mov_b32_e32 v160, v170
	v_mov_b32_e32 v161, v188
	v_mov_b32_e32 v188, v171
	v_mov_b32_e32 v168, v190
	v_mov_b32_e32 v169, v194
	v_mov_b32_e32 v194, v191
	v_mov_b32_e32 v170, v192
	v_mov_b32_e32 v171, v196
	v_mov_b32_e32 v196, v193
	v_mov_b32_e32 v190, v198
	v_mov_b32_e32 v191, v202
	v_mov_b32_e32 v202, v199
	v_mov_b32_e32 v192, v200
	v_mov_b32_e32 v193, v204
	v_mov_b32_e32 v204, v201
	v_mov_b32_e32 v198, v206
	v_mov_b32_e32 v199, v214
	v_mov_b32_e32 v214, v207
	v_mov_b32_e32 v200, v208
	v_mov_b32_e32 v201, v216
	v_mov_b32_e32 v216, v209
	v_pk_add_f32 v[154:155], v[154:155], v[186:187]
	v_pk_add_f32 v[160:161], v[160:161], v[188:189]
	v_pk_add_f32 v[168:169], v[168:169], v[194:195]
	v_pk_add_f32 v[170:171], v[170:171], v[196:197]
	v_pk_add_f32 v[186:187], v[190:191], v[202:203]
	v_pk_add_f32 v[188:189], v[192:193], v[204:205]
	v_pk_add_f32 v[190:191], v[198:199], v[214:215]
	v_pk_add_f32 v[192:193], v[200:201], v[216:217]
	v_pk_add_f32 v[154:155], v[154:155], v[160:161]
	v_pk_add_f32 v[160:161], v[168:169], v[170:171]
	v_pk_add_f32 v[168:169], v[186:187], v[188:189]
	v_pk_add_f32 v[170:171], v[190:191], v[192:193]
	v_pk_add_f32 v[154:155], v[154:155], v[160:161]
	v_pk_add_f32 v[160:161], v[168:169], v[170:171]
	ds_bpermute_b32 v168, v180, v154
	ds_bpermute_b32 v169, v180, v155
	ds_bpermute_b32 v170, v180, v160
	ds_bpermute_b32 v171, v180, v161
	v_mov_b32_e32 v206, v218
	v_mov_b32_e32 v207, v222
	s_waitcnt lgkmcnt(2)
	v_pk_add_f32 v[154:155], v[154:155], v[168:169]
	ds_bpermute_b32 v168, v181, v154
	ds_bpermute_b32 v169, v181, v155
	v_mov_b32_e32 v222, v219
	v_mov_b32_e32 v186, v220
	v_mov_b32_e32 v187, v224
	v_mov_b32_e32 v224, v221
	v_pk_add_f32 v[188:189], v[206:207], v[222:223]
	v_pk_add_f32 v[186:187], v[186:187], v[224:225]
	s_waitcnt lgkmcnt(0)
	v_pk_add_f32 v[154:155], v[154:155], v[168:169]
	v_pk_add_f32 v[160:161], v[160:161], v[170:171]
	v_pk_fma_f32 v[154:155], v[154:155], s[26:27], v[164:165] op_sel_hi:[1,0,0]
	v_pk_add_f32 v[186:187], v[188:189], v[186:187]
	v_mov_b32_e32 v188, v226
	v_mov_b32_e32 v189, v230
	v_mov_b32_e32 v230, v227
	v_mov_b32_e32 v190, v228
	v_mov_b32_e32 v191, v232
	v_mov_b32_e32 v232, v229
	ds_bpermute_b32 v170, v181, v160
	ds_bpermute_b32 v171, v181, v161
	v_mul_f32_e32 v168, 0x4b800000, v154
	v_mul_f32_e32 v169, 0x4b800000, v155
	v_cmp_gt_f32_e32 vcc, s63, v154
	v_cmp_gt_f32_e64 s[0:1], s63, v155
	v_pk_add_f32 v[188:189], v[188:189], v[230:231]
	v_pk_add_f32 v[190:191], v[190:191], v[232:233]
	v_cndmask_b32_e32 v154, v154, v168, vcc
	v_cndmask_b32_e64 v155, v155, v169, s[0:1]
	v_pk_add_f32 v[188:189], v[188:189], v[190:191]
	v_rsq_f32_e32 v154, v154
	v_rsq_f32_e32 v155, v155
	v_pk_add_f32 v[186:187], v[186:187], v[188:189]
	ds_bpermute_b32 v188, v180, v186
	ds_bpermute_b32 v189, v180, v187
	s_waitcnt lgkmcnt(2)
	v_pk_add_f32 v[160:161], v[160:161], v[170:171]
	v_pk_mul_f32 v[168:169], v[154:155], s[36:37] op_sel_hi:[1,0]
	v_pk_fma_f32 v[160:161], v[160:161], s[26:27], v[164:165] op_sel_hi:[1,0,0]
	v_cndmask_b32_e64 v171, v155, v169, s[0:1]
	v_mul_f32_e32 v170, 0x4b800000, v160
	v_cmp_gt_f32_e64 s[8:9], s63, v160
	v_mul_f32_e32 v155, 0x4b800000, v161
	v_cmp_gt_f32_e64 s[0:1], s63, v161
	v_cndmask_b32_e64 v160, v160, v170, s[8:9]
	s_waitcnt lgkmcnt(0)
	v_pk_add_f32 v[186:187], v[186:187], v[188:189]
	v_cndmask_b32_e64 v155, v161, v155, s[0:1]
	v_rsq_f32_e32 v160, v160
	v_rsq_f32_e32 v161, v155
	ds_bpermute_b32 v188, v181, v186
	ds_bpermute_b32 v189, v181, v187
	v_cndmask_b32_e32 v170, v154, v168, vcc
	v_pk_mul_f32 v[154:155], v[160:161], s[36:37] op_sel_hi:[1,0]
	s_nop 0
	v_cndmask_b32_e64 v169, v161, v155, s[0:1]
	v_cndmask_b32_e64 v168, v160, v154, s[8:9]
	s_waitcnt lgkmcnt(0)
	v_pk_add_f32 v[154:155], v[186:187], v[188:189]
	v_mov_b32_e32 v160, v238
	v_mov_b32_e32 v161, v246
	v_mov_b32_e32 v246, v239
	v_mov_b32_e32 v186, v240
	v_mov_b32_e32 v187, v248
	v_mov_b32_e32 v248, v241
	v_pk_add_f32 v[160:161], v[160:161], v[246:247]
	v_pk_add_f32 v[186:187], v[186:187], v[248:249]
	v_mov_b32_e32 v188, v236
	v_pk_add_f32 v[160:161], v[160:161], v[186:187]
	v_mov_b32_e32 v186, v234
	v_mov_b32_e32 v187, v242
	v_mov_b32_e32 v242, v235
	v_mov_b32_e32 v189, v244
	v_mov_b32_e32 v244, v237
	v_pk_add_f32 v[186:187], v[186:187], v[242:243]
	v_pk_add_f32 v[188:189], v[188:189], v[244:245]
	v_pk_fma_f32 v[154:155], v[154:155], s[26:27], v[164:165] op_sel_hi:[1,0,0]
	v_pk_add_f32 v[186:187], v[186:187], v[188:189]
	v_mul_f32_e32 v188, 0x4b800000, v154
	v_pk_add_f32 v[160:161], v[160:161], v[186:187]
	ds_bpermute_b32 v186, v180, v160
	ds_bpermute_b32 v187, v180, v161
	v_cmp_gt_f32_e32 vcc, s63, v154
	v_cmp_gt_f32_e64 s[0:1], s63, v155
	s_waitcnt lgkmcnt(0)
	v_pk_add_f32 v[160:161], v[160:161], v[186:187]
	ds_bpermute_b32 v186, v181, v160
	ds_bpermute_b32 v187, v181, v161
	v_cndmask_b32_e32 v154, v154, v188, vcc
	v_mul_f32_e32 v188, 0x4b800000, v155
	v_cndmask_b32_e64 v155, v155, v188, s[0:1]
	v_rsq_f32_e32 v154, v154
	s_waitcnt lgkmcnt(0)
	v_pk_add_f32 v[160:161], v[160:161], v[186:187]
	v_rsq_f32_e32 v155, v155
	v_pk_fma_f32 v[160:161], v[160:161], s[26:27], v[164:165] op_sel_hi:[1,0,0]
	s_nop 0
	v_mul_f32_e32 v164, 0x4b800000, v160
	v_cmp_gt_f32_e64 s[8:9], s63, v160
	v_cmp_gt_f32_e64 s[12:13], s63, v161
	s_nop 0
	v_cndmask_b32_e64 v160, v160, v164, s[8:9]
	v_rsq_f32_e32 v164, v160
	v_mul_f32_e32 v160, 0x4b800000, v161
	v_cndmask_b32_e64 v160, v161, v160, s[12:13]
	v_rsq_f32_e32 v165, v160
	v_pk_mul_f32 v[160:161], v[154:155], s[36:37] op_sel_hi:[1,0]
	s_nop 0
	v_cndmask_b32_e64 v161, v155, v161, s[0:1]
	v_cndmask_b32_e32 v160, v154, v160, vcc
	v_pk_mul_f32 v[154:155], v[164:165], s[36:37] op_sel_hi:[1,0]
	s_mov_b64 s[0:1], 0
	v_cndmask_b32_e64 v155, v165, v155, s[12:13]
	v_cndmask_b32_e64 v154, v164, v154, s[8:9]
